# feat_b: seventh-round half-items moved from workgroups 0..47 to workgroups 208..255
# baseline (speedup 1.0000x reference)
; DI void phase_feat_b(KP p, int l, char* lds) {
;     ...
;   for (int it = 2 * blockIdx.x + hbb; it < N1 + N2 + N3 + N4; it += 2 * gridDim.x) {
;     if (it < N1) {
.LBB0_218:
	v_readlane_b32 s2, v253, 8
	s_add_i32 s20, s20, s2
	v_readlane_b32 s2, v254, 52
	s_add_i32 s75, s75, s2
	s_sub_u32 s2, s20, 0xc00
	s_cmp_lt_u32 s2, 0x60
	s_cbranch_scc0 .Lfb_hi
	s_movk_i32 s20, 0x7fff
	s_branch .Lfb_done
.Lfb_hi:
	s_sub_u32 s2, s20, 0xda0
	s_cmp_lt_u32 s2, 0x60
	s_cbranch_scc0 .Lfb_done
	s_sub_i32 s20, s20, 0x1a0
	s_sub_i32 s75, s75, 0x6800
.Lfb_done:
	s_cmpk_gt_i32 s20, 0xc5f
	s_cbranch_scc1 .LBB0_255
